# P6 K-loop rewritten by hand: one 64-MFMA block per K-tile and half (2 barriers per K-tile instead of 4), second A half read inside the block, role-split LDS staging; on top of v22
# baseline (speedup 1.0000x reference)
.LBB0_730:
	s_add_i32 s38, s38, 1
	v_readlane_b32 s5, v243, 0
	s_mul_i32 s0, s38, s42
	s_mul_hi_u32 s1, s38, s5
	s_add_i32 s1, s1, s0
	s_mul_i32 s0, s38, s5
	s_mov_b64 s[22:23], s[12:13]
	s_add_u32 s12, s0, s94
	s_addc_u32 s13, s1, s43
	v_cmp_lt_i64_e64 s[0:1], s[12:13], v[146:147]
	s_mov_b64 s[24:25], s[14:15]
	s_and_b64 s[14:15], s[0:1], exec
	s_cselect_b32 s5, s12, 0
	s_ashr_i32 s14, s5, 31
	s_lshr_b32 s14, s14, 29
	s_add_i32 s14, s5, s14
	s_ashr_i32 s15, s14, 3
	s_and_b32 s14, s14, -8
	s_sub_i32 s5, s5, s14
	s_cmp_lt_i32 s5, 0
	s_cselect_b32 s14, s33, 0x183
	s_mul_i32 s5, s5, s14
	s_add_i32 s5, s5, s15
	s_mul_hi_i32 s14, s5, 0x2fa0be83
	s_lshr_b32 s15, s14, 31
	s_ashr_i32 s14, s14, 7
	s_add_i32 s14, s14, s15
	s_lshl_b32 s15, s14, 3
	s_sub_i32 s21, 36, s15
	s_min_i32 s21, s21, 8
	s_abs_i32 s57, s21
	v_cvt_f32_u32_e32 v2, s57
	s_mulk_i32 s14, 0x2b0
	s_mov_b32 s56, s4
	v_cmp_gt_i64_e32 vcc, s[12:13], v[144:145]
	v_rcp_iflag_f32_e32 v2, v2
	s_sub_i32 s4, s5, s14
	s_sub_i32 s13, 0, s57
	s_abs_i32 s12, s4
	v_mul_f32_e32 v2, 0x4f7ffffe, v2
	v_cvt_u32_f32_e32 v2, v2
	s_xor_b32 s5, s4, s21
	s_mov_b32 s55, s20
	s_ashr_i32 s5, s5, 31
	v_readfirstlane_b32 s14, v2
	s_mul_i32 s13, s13, s14
	s_mul_hi_u32 s13, s14, s13
	s_add_i32 s14, s14, s13
	s_mul_hi_u32 s13, s12, s14
	s_mul_i32 s14, s13, s57
	s_sub_i32 s12, s12, s14
	s_add_i32 s14, s13, 1
	s_sub_i32 s20, s12, s57
	s_cmp_ge_u32 s12, s57
	s_cselect_b32 s13, s14, s13
	s_cselect_b32 s12, s20, s12
	s_add_i32 s14, s13, 1
	s_cmp_ge_u32 s12, s57
	s_cselect_b32 s12, s14, s13
	s_xor_b32 s12, s12, s5
	s_sub_i32 s20, s12, s5
	s_mul_i32 s5, s20, s21
	s_sub_i32 s4, s4, s5
	s_add_i32 s4, s15, s4
	s_ashr_i32 s5, s4, 31
	s_lshl_b64 s[12:13], s[4:5], 21
	s_add_u32 s14, s27, s12
	s_addc_u32 s15, s28, s13
	s_and_b64 s[12:13], s[0:1], exec
	s_cselect_b32 s5, s15, s25
	s_cselect_b32 s57, s14, s24
	s_ashr_i32 s21, s20, 31
	s_lshl_b64 s[12:13], s[20:21], 21
	s_add_u32 s12, s29, s12
	s_addc_u32 s13, s30, s13
	s_and_b64 s[0:1], s[0:1], exec
	s_cselect_b32 s21, s13, s23
	s_cselect_b32 s58, s12, s22
	s_add_u32 s0, s24, 0x100080
	s_addc_u32 s1, s25, 0
	s_add_u32 s59, s22, 0x100
	v_mov_b32_e32 v2, 0
	s_addc_u32 s60, s23, 0
	s_mov_b32 s61, -2
	v_mov_b32_e32 v3, v2
	v_mov_b32_e32 v4, v2
	v_mov_b32_e32 v5, v2
	v_mov_b32_e32 v6, v2
	v_mov_b32_e32 v7, v2
	v_mov_b32_e32 v8, v2
	v_mov_b32_e32 v9, v2
	v_mov_b32_e32 v18, v2
	v_mov_b32_e32 v19, v2
	v_mov_b32_e32 v20, v2
	v_mov_b32_e32 v21, v2
	v_mov_b32_e32 v22, v2
	v_mov_b32_e32 v23, v2
	v_mov_b32_e32 v24, v2
	v_mov_b32_e32 v25, v2
	v_mov_b32_e32 v34, v2
	v_mov_b32_e32 v35, v2
	v_mov_b32_e32 v36, v2
	v_mov_b32_e32 v37, v2
	v_mov_b32_e32 v38, v2
	v_mov_b32_e32 v39, v2
	v_mov_b32_e32 v40, v2
	v_mov_b32_e32 v41, v2
	v_mov_b32_e32 v50, v2
	v_mov_b32_e32 v51, v2
	v_mov_b32_e32 v52, v2
	v_mov_b32_e32 v53, v2
	v_mov_b32_e32 v54, v2
	v_mov_b32_e32 v55, v2
	v_mov_b32_e32 v56, v2
	v_mov_b32_e32 v57, v2
	v_mov_b32_e32 v10, v2
	v_mov_b32_e32 v11, v2
	v_mov_b32_e32 v12, v2
	v_mov_b32_e32 v13, v2
	v_mov_b32_e32 v14, v2
	v_mov_b32_e32 v15, v2
	v_mov_b32_e32 v16, v2
	v_mov_b32_e32 v17, v2
	v_mov_b32_e32 v26, v2
	v_mov_b32_e32 v27, v2
	v_mov_b32_e32 v28, v2
	v_mov_b32_e32 v29, v2
	v_mov_b32_e32 v30, v2
	v_mov_b32_e32 v31, v2
	v_mov_b32_e32 v32, v2
	v_mov_b32_e32 v33, v2
	v_mov_b32_e32 v42, v2
	v_mov_b32_e32 v43, v2
	v_mov_b32_e32 v44, v2
	v_mov_b32_e32 v45, v2
	v_mov_b32_e32 v46, v2
	v_mov_b32_e32 v47, v2
	v_mov_b32_e32 v48, v2
	v_mov_b32_e32 v49, v2
	v_mov_b32_e32 v58, v2
	v_mov_b32_e32 v59, v2
	v_mov_b32_e32 v60, v2
	v_mov_b32_e32 v61, v2
	v_mov_b32_e32 v62, v2
	v_mov_b32_e32 v63, v2
	v_mov_b32_e32 v64, v2
	v_mov_b32_e32 v65, v2
	v_mov_b32_e32 v66, v2
	v_mov_b32_e32 v67, v2
	v_mov_b32_e32 v68, v2
	v_mov_b32_e32 v69, v2
	v_mov_b32_e32 v70, v2
	v_mov_b32_e32 v71, v2
	v_mov_b32_e32 v72, v2
	v_mov_b32_e32 v73, v2
	v_mov_b32_e32 v82, v2
	v_mov_b32_e32 v83, v2
	v_mov_b32_e32 v84, v2
	v_mov_b32_e32 v85, v2
	v_mov_b32_e32 v86, v2
	v_mov_b32_e32 v87, v2
	v_mov_b32_e32 v88, v2
	v_mov_b32_e32 v89, v2
	v_mov_b32_e32 v98, v2
	v_mov_b32_e32 v99, v2
	v_mov_b32_e32 v100, v2
	v_mov_b32_e32 v101, v2
	v_mov_b32_e32 v102, v2
	v_mov_b32_e32 v103, v2
	v_mov_b32_e32 v104, v2
	v_mov_b32_e32 v105, v2
	v_mov_b32_e32 v114, v2
	v_mov_b32_e32 v115, v2
	v_mov_b32_e32 v116, v2
	v_mov_b32_e32 v117, v2
	v_mov_b32_e32 v118, v2
	v_mov_b32_e32 v119, v2
	v_mov_b32_e32 v120, v2
	v_mov_b32_e32 v121, v2
	v_mov_b32_e32 v74, v2
	v_mov_b32_e32 v75, v2
	v_mov_b32_e32 v76, v2
	v_mov_b32_e32 v77, v2
	v_mov_b32_e32 v78, v2
	v_mov_b32_e32 v79, v2
	v_mov_b32_e32 v80, v2
	v_mov_b32_e32 v81, v2
	v_mov_b32_e32 v90, v2
	v_mov_b32_e32 v91, v2
	v_mov_b32_e32 v92, v2
	v_mov_b32_e32 v93, v2
	v_mov_b32_e32 v94, v2
	v_mov_b32_e32 v95, v2
	v_mov_b32_e32 v96, v2
	v_mov_b32_e32 v97, v2
	v_mov_b32_e32 v106, v2
	v_mov_b32_e32 v107, v2
	v_mov_b32_e32 v108, v2
	v_mov_b32_e32 v109, v2
	v_mov_b32_e32 v110, v2
	v_mov_b32_e32 v111, v2
	v_mov_b32_e32 v112, v2
	v_mov_b32_e32 v113, v2
	v_mov_b32_e32 v122, v2
	v_mov_b32_e32 v123, v2
	v_mov_b32_e32 v124, v2
	v_mov_b32_e32 v125, v2
	v_mov_b32_e32 v126, v2
	v_mov_b32_e32 v127, v2
	v_mov_b32_e32 v128, v2
	v_mov_b32_e32 v129, v2
	s_bfe_u32 s70, s31, 0x2000a
	s_lshl_b32 s68, s70, 17
	s_lshl_b32 s69, s70, 18
	s_lshl_b32 s71, s70, 12
	s_lshl_b32 s70, s70, 11
	v_lshlrev_b32_e32 v152, 4, v174
	v_bfe_u32 v153, v152, 9, 1
	v_lshlrev_b32_e32 v153, 5, v153
	v_xor_b32_e32 v152, v152, v153
	v_lshrrev_b32_e32 v153, 6, v152
	v_and_b32_e32 v152, 63, v152
	v_lshl_or_b32 v140, v153, 13, v152
	v_lshrrev_b32_e32 v159, 2, v153
	v_and_b32_e32 v153, 3, v153
	v_lshl_or_b32 v159, v159, 3, v153
	v_lshl_or_b32 v142, v159, 13, v152
	v_mov_b32_e32 v141, 0
	v_mov_b32_e32 v143, 0
.LBB0_731:
	s_add_u32 s72, s24, 0x100
	s_addc_u32 s73, s25, 0
	s_add_u32 s74, s22, 0x100
	s_addc_u32 s75, s23, 0
	s_cmp_eq_u32 s61, 60
	s_cselect_b32 s72, s57, s72
	s_cselect_b32 s73, s5, s73
	s_cselect_b32 s74, s58, s74
	s_cselect_b32 s75, s21, s75
	s_add_u32 s72, s72, s68
	s_addc_u32 s73, s73, 0
	s_add_u32 s74, s74, s69
	s_addc_u32 s75, s75, 0
	s_add_u32 s96, s24, s68
	s_addc_u32 s97, s25, 0
	s_add_u32 s96, s96, 0x80
	s_addc_u32 s97, s97, 0
	s_add_u32 s100, s22, s69
	s_addc_u32 s101, s23, 0
	s_add_u32 s100, s100, 0x80
	s_addc_u32 s101, s101, 0
	s_cmpk_gt_u32 s26, 0xff
	s_cbranch_scc1 .Lm64_Ta
	s_add_i32 m0, s70, 0xc000
	s_add_u32 s62, s96, 0x100000
	s_addc_u32 s63, s97, 0
	v_lshl_add_u64 v[152:153], s[62:63], 0, v[140:141]
	global_load_lds_dwordx4 v[152:153], off
	s_add_i32 m0, s70, 0xc400
	s_add_u32 s62, s96, 0x100040
	s_addc_u32 s63, s97, 0
	v_lshl_add_u64 v[152:153], s[62:63], 0, v[140:141]
	global_load_lds_dwordx4 v[152:153], off
	s_add_i32 m0, s70, 0xa000
	s_add_u32 s62, s96, 0x80000
	s_addc_u32 s63, s97, 0
	v_lshl_add_u64 v[152:153], s[62:63], 0, v[140:141]
	global_load_lds_dwordx4 v[152:153], off
	s_add_i32 m0, s70, 0xa400
	s_add_u32 s62, s96, 0x80040
	s_addc_u32 s63, s97, 0
	v_lshl_add_u64 v[152:153], s[62:63], 0, v[140:141]
	global_load_lds_dwordx4 v[152:153], off
	s_add_i32 m0, s71, 0x1c000
	s_add_u32 s62, s100, 0x100000
	s_addc_u32 s63, s101, 0
	v_lshl_add_u64 v[152:153], s[62:63], 0, v[142:143]
	global_load_lds_dwordx4 v[152:153], off
	s_add_i32 m0, s71, 0x1c400
	s_add_u32 s62, s100, 0x100040
	s_addc_u32 s63, s101, 0
	v_lshl_add_u64 v[152:153], s[62:63], 0, v[142:143]
	global_load_lds_dwordx4 v[152:153], off
	s_add_i32 m0, s71, 0x1c800
	s_add_u32 s62, s100, 0x108000
	s_addc_u32 s63, s101, 0
	v_lshl_add_u64 v[152:153], s[62:63], 0, v[142:143]
	global_load_lds_dwordx4 v[152:153], off
	s_add_i32 m0, s71, 0x1cc00
	s_add_u32 s62, s100, 0x108040
	s_addc_u32 s63, s101, 0
	v_lshl_add_u64 v[152:153], s[62:63], 0, v[142:143]
	global_load_lds_dwordx4 v[152:153], off
	s_waitcnt vmcnt(8)
	ds_read_b128 v[148:151], v156
	ds_read_b128 v[160:163], v156 offset:1024
	ds_read_b128 v[164:167], v156 offset:2048
	ds_read_b128 v[168:171], v156 offset:3072
	ds_read_b128 v[176:179], v157
	ds_read_b128 v[180:183], v157 offset:1024
	ds_read_b128 v[184:187], v157 offset:2048
	ds_read_b128 v[188:191], v157 offset:3072
	ds_read_b128 v[192:195], v158
	ds_read_b128 v[196:199], v158 offset:1024
	ds_read_b128 v[200:203], v158 offset:2048
	ds_read_b128 v[204:207], v158 offset:3072
	ds_read_b128 v[208:211], v158 offset:4096
	ds_read_b128 v[212:215], v158 offset:5120
	ds_read_b128 v[216:219], v158 offset:6144
	ds_read_b128 v[220:223], v158 offset:7168
	s_waitcnt lgkmcnt(0)
	s_branch .Lm64_Ja
.Lm64_Ta:
	s_add_i32 m0, s70, 0x0
	s_add_u32 s62, s72, 0x0
	s_addc_u32 s63, s73, 0
	v_lshl_add_u64 v[152:153], s[62:63], 0, v[140:141]
	global_load_lds_dwordx4 v[152:153], off
	s_add_i32 m0, s70, 0x400
	s_add_u32 s62, s72, 0x40
	s_addc_u32 s63, s73, 0
	v_lshl_add_u64 v[152:153], s[62:63], 0, v[140:141]
	global_load_lds_dwordx4 v[152:153], off
	s_add_i32 m0, s70, 0xe000
	s_add_u32 s62, s96, 0x180000
	s_addc_u32 s63, s97, 0
	v_lshl_add_u64 v[152:153], s[62:63], 0, v[140:141]
	global_load_lds_dwordx4 v[152:153], off
	s_add_i32 m0, s70, 0xe400
	s_add_u32 s62, s96, 0x180040
	s_addc_u32 s63, s97, 0
	v_lshl_add_u64 v[152:153], s[62:63], 0, v[140:141]
	global_load_lds_dwordx4 v[152:153], off
	ds_read_b128 v[148:151], v156
	ds_read_b128 v[160:163], v156 offset:1024
	ds_read_b128 v[164:167], v156 offset:2048
	ds_read_b128 v[168:171], v156 offset:3072
	ds_read_b128 v[176:179], v157
	ds_read_b128 v[180:183], v157 offset:1024
	ds_read_b128 v[184:187], v157 offset:2048
	ds_read_b128 v[188:191], v157 offset:3072
	ds_read_b128 v[192:195], v158
	ds_read_b128 v[196:199], v158 offset:1024
	ds_read_b128 v[200:203], v158 offset:2048
	ds_read_b128 v[204:207], v158 offset:3072
	ds_read_b128 v[208:211], v158 offset:4096
	ds_read_b128 v[212:215], v158 offset:5120
	ds_read_b128 v[216:219], v158 offset:6144
	ds_read_b128 v[220:223], v158 offset:7168
	s_waitcnt lgkmcnt(0)
	s_add_i32 m0, s71, 0x10000
	s_add_u32 s62, s74, 0x0
	s_addc_u32 s63, s75, 0
	v_lshl_add_u64 v[152:153], s[62:63], 0, v[142:143]
	global_load_lds_dwordx4 v[152:153], off
	s_add_i32 m0, s71, 0x10400
	s_add_u32 s62, s74, 0x40
	s_addc_u32 s63, s75, 0
	v_lshl_add_u64 v[152:153], s[62:63], 0, v[142:143]
	global_load_lds_dwordx4 v[152:153], off
	s_add_i32 m0, s71, 0x10800
	s_add_u32 s62, s74, 0x8000
	s_addc_u32 s63, s75, 0
	v_lshl_add_u64 v[152:153], s[62:63], 0, v[142:143]
	global_load_lds_dwordx4 v[152:153], off
	s_add_i32 m0, s71, 0x10c00
	s_add_u32 s62, s74, 0x8040
	s_addc_u32 s63, s75, 0
	v_lshl_add_u64 v[152:153], s[62:63], 0, v[142:143]
	global_load_lds_dwordx4 v[152:153], off
	s_waitcnt vmcnt(8)
.Lm64_Ja:
	s_barrier
	s_setprio 1
	v_mfma_f32_16x16x32_bf16 v[126:129], v[148:151], v[192:195], v[126:129]
	v_mfma_f32_16x16x32_bf16 v[122:125], v[164:167], v[192:195], v[122:125]
	v_mfma_f32_16x16x32_bf16 v[110:113], v[148:151], v[200:203], v[110:113]
	v_mfma_f32_16x16x32_bf16 v[106:109], v[164:167], v[200:203], v[106:109]
	v_mfma_f32_16x16x32_bf16 v[94:97], v[148:151], v[208:211], v[94:97]
	v_mfma_f32_16x16x32_bf16 v[90:93], v[164:167], v[208:211], v[90:93]
	v_mfma_f32_16x16x32_bf16 v[78:81], v[148:151], v[216:219], v[78:81]
	v_mfma_f32_16x16x32_bf16 v[74:77], v[164:167], v[216:219], v[74:77]
	v_mfma_f32_16x16x32_bf16 v[126:129], v[160:163], v[196:199], v[126:129]
	v_mfma_f32_16x16x32_bf16 v[122:125], v[168:171], v[196:199], v[122:125]
	v_mfma_f32_16x16x32_bf16 v[110:113], v[160:163], v[204:207], v[110:113]
	v_mfma_f32_16x16x32_bf16 v[106:109], v[168:171], v[204:207], v[106:109]
	v_mfma_f32_16x16x32_bf16 v[94:97], v[160:163], v[212:215], v[94:97]
	v_mfma_f32_16x16x32_bf16 v[90:93], v[168:171], v[212:215], v[90:93]
	v_mfma_f32_16x16x32_bf16 v[78:81], v[160:163], v[220:223], v[78:81]
	v_mfma_f32_16x16x32_bf16 v[74:77], v[168:171], v[220:223], v[74:77]
	v_mfma_f32_16x16x32_bf16 v[118:121], v[176:179], v[192:195], v[118:121]
	v_mfma_f32_16x16x32_bf16 v[114:117], v[184:187], v[192:195], v[114:117]
	v_mfma_f32_16x16x32_bf16 v[118:121], v[180:183], v[196:199], v[118:121]
	v_mfma_f32_16x16x32_bf16 v[114:117], v[188:191], v[196:199], v[114:117]
	ds_read_b128 v[192:195], v158 offset:16384
	ds_read_b128 v[196:199], v158 offset:17408
	v_mfma_f32_16x16x32_bf16 v[102:105], v[176:179], v[200:203], v[102:105]
	v_mfma_f32_16x16x32_bf16 v[98:101], v[184:187], v[200:203], v[98:101]
	v_mfma_f32_16x16x32_bf16 v[102:105], v[180:183], v[204:207], v[102:105]
	v_mfma_f32_16x16x32_bf16 v[98:101], v[188:191], v[204:207], v[98:101]
	ds_read_b128 v[200:203], v158 offset:18432
	ds_read_b128 v[204:207], v158 offset:19456
	v_mfma_f32_16x16x32_bf16 v[86:89], v[176:179], v[208:211], v[86:89]
	v_mfma_f32_16x16x32_bf16 v[82:85], v[184:187], v[208:211], v[82:85]
	v_mfma_f32_16x16x32_bf16 v[86:89], v[180:183], v[212:215], v[86:89]
	v_mfma_f32_16x16x32_bf16 v[82:85], v[188:191], v[212:215], v[82:85]
	ds_read_b128 v[208:211], v158 offset:20480
	ds_read_b128 v[212:215], v158 offset:21504
	v_mfma_f32_16x16x32_bf16 v[70:73], v[176:179], v[216:219], v[70:73]
	v_mfma_f32_16x16x32_bf16 v[66:69], v[184:187], v[216:219], v[66:69]
	v_mfma_f32_16x16x32_bf16 v[70:73], v[180:183], v[220:223], v[70:73]
	v_mfma_f32_16x16x32_bf16 v[66:69], v[188:191], v[220:223], v[66:69]
	ds_read_b128 v[216:219], v158 offset:22528
	ds_read_b128 v[220:223], v158 offset:23552
	s_waitcnt lgkmcnt(6)
	v_mfma_f32_16x16x32_bf16 v[62:65], v[148:151], v[192:195], v[62:65]
	v_mfma_f32_16x16x32_bf16 v[58:61], v[164:167], v[192:195], v[58:61]
	v_mfma_f32_16x16x32_bf16 v[62:65], v[160:163], v[196:199], v[62:65]
	v_mfma_f32_16x16x32_bf16 v[58:61], v[168:171], v[196:199], v[58:61]
	s_waitcnt lgkmcnt(4)
	v_mfma_f32_16x16x32_bf16 v[46:49], v[148:151], v[200:203], v[46:49]
	v_mfma_f32_16x16x32_bf16 v[42:45], v[164:167], v[200:203], v[42:45]
	v_mfma_f32_16x16x32_bf16 v[46:49], v[160:163], v[204:207], v[46:49]
	v_mfma_f32_16x16x32_bf16 v[42:45], v[168:171], v[204:207], v[42:45]
	s_waitcnt lgkmcnt(2)
	v_mfma_f32_16x16x32_bf16 v[30:33], v[148:151], v[208:211], v[30:33]
	v_mfma_f32_16x16x32_bf16 v[26:29], v[164:167], v[208:211], v[26:29]
	v_mfma_f32_16x16x32_bf16 v[30:33], v[160:163], v[212:215], v[30:33]
	v_mfma_f32_16x16x32_bf16 v[26:29], v[168:171], v[212:215], v[26:29]
	s_waitcnt lgkmcnt(0)
	v_mfma_f32_16x16x32_bf16 v[14:17], v[148:151], v[216:219], v[14:17]
	v_mfma_f32_16x16x32_bf16 v[10:13], v[164:167], v[216:219], v[10:13]
	v_mfma_f32_16x16x32_bf16 v[14:17], v[160:163], v[220:223], v[14:17]
	v_mfma_f32_16x16x32_bf16 v[10:13], v[168:171], v[220:223], v[10:13]
	v_mfma_f32_16x16x32_bf16 v[54:57], v[176:179], v[192:195], v[54:57]
	v_mfma_f32_16x16x32_bf16 v[50:53], v[184:187], v[192:195], v[50:53]
	v_mfma_f32_16x16x32_bf16 v[38:41], v[176:179], v[200:203], v[38:41]
	v_mfma_f32_16x16x32_bf16 v[34:37], v[184:187], v[200:203], v[34:37]
	v_mfma_f32_16x16x32_bf16 v[22:25], v[176:179], v[208:211], v[22:25]
	v_mfma_f32_16x16x32_bf16 v[18:21], v[184:187], v[208:211], v[18:21]
	v_mfma_f32_16x16x32_bf16 v[6:9], v[176:179], v[216:219], v[6:9]
	v_mfma_f32_16x16x32_bf16 v[2:5], v[184:187], v[216:219], v[2:5]
	v_mfma_f32_16x16x32_bf16 v[54:57], v[180:183], v[196:199], v[54:57]
	v_mfma_f32_16x16x32_bf16 v[50:53], v[188:191], v[196:199], v[50:53]
	v_mfma_f32_16x16x32_bf16 v[38:41], v[180:183], v[204:207], v[38:41]
	v_mfma_f32_16x16x32_bf16 v[34:37], v[188:191], v[204:207], v[34:37]
	v_mfma_f32_16x16x32_bf16 v[22:25], v[180:183], v[212:215], v[22:25]
	v_mfma_f32_16x16x32_bf16 v[18:21], v[188:191], v[212:215], v[18:21]
	v_mfma_f32_16x16x32_bf16 v[6:9], v[180:183], v[220:223], v[6:9]
	v_mfma_f32_16x16x32_bf16 v[2:5], v[188:191], v[220:223], v[2:5]
	s_setprio 0
	s_barrier
	s_cmpk_gt_u32 s26, 0xff
	s_cbranch_scc1 .Lm64_Tb
	s_add_i32 m0, s70, 0x4000
	s_add_u32 s62, s72, 0x100000
	s_addc_u32 s63, s73, 0
	v_lshl_add_u64 v[152:153], s[62:63], 0, v[140:141]
	global_load_lds_dwordx4 v[152:153], off
	s_add_i32 m0, s70, 0x4400
	s_add_u32 s62, s72, 0x100040
	s_addc_u32 s63, s73, 0
	v_lshl_add_u64 v[152:153], s[62:63], 0, v[140:141]
	global_load_lds_dwordx4 v[152:153], off
	s_add_i32 m0, s70, 0x2000
	s_add_u32 s62, s72, 0x80000
	s_addc_u32 s63, s73, 0
	v_lshl_add_u64 v[152:153], s[62:63], 0, v[140:141]
	global_load_lds_dwordx4 v[152:153], off
	s_add_i32 m0, s70, 0x2400
	s_add_u32 s62, s72, 0x80040
	s_addc_u32 s63, s73, 0
	v_lshl_add_u64 v[152:153], s[62:63], 0, v[140:141]
	global_load_lds_dwordx4 v[152:153], off
	s_add_i32 m0, s71, 0x14000
	s_add_u32 s62, s74, 0x100000
	s_addc_u32 s63, s75, 0
	v_lshl_add_u64 v[152:153], s[62:63], 0, v[142:143]
	global_load_lds_dwordx4 v[152:153], off
	s_add_i32 m0, s71, 0x14400
	s_add_u32 s62, s74, 0x100040
	s_addc_u32 s63, s75, 0
	v_lshl_add_u64 v[152:153], s[62:63], 0, v[142:143]
	global_load_lds_dwordx4 v[152:153], off
	s_add_i32 m0, s71, 0x14800
	s_add_u32 s62, s74, 0x108000
	s_addc_u32 s63, s75, 0
	v_lshl_add_u64 v[152:153], s[62:63], 0, v[142:143]
	global_load_lds_dwordx4 v[152:153], off
	s_add_i32 m0, s71, 0x14c00
	s_add_u32 s62, s74, 0x108040
	s_addc_u32 s63, s75, 0
	v_lshl_add_u64 v[152:153], s[62:63], 0, v[142:143]
	global_load_lds_dwordx4 v[152:153], off
	s_waitcnt vmcnt(8)
	v_add_u32_e32 v159, 0x18000, v135
	ds_read_b128 v[148:151], v159
	ds_read_b128 v[160:163], v159 offset:1024
	ds_read_b128 v[164:167], v159 offset:2048
	ds_read_b128 v[168:171], v159 offset:3072
	v_add_u32_e32 v159, 0x1c000, v135
	ds_read_b128 v[176:179], v159
	ds_read_b128 v[180:183], v159 offset:1024
	ds_read_b128 v[184:187], v159 offset:2048
	ds_read_b128 v[188:191], v159 offset:3072
	ds_read_b128 v[192:195], v158 offset:32768
	ds_read_b128 v[196:199], v158 offset:33792
	ds_read_b128 v[200:203], v158 offset:34816
	ds_read_b128 v[204:207], v158 offset:35840
	ds_read_b128 v[208:211], v158 offset:36864
	ds_read_b128 v[212:215], v158 offset:37888
	ds_read_b128 v[216:219], v158 offset:38912
	ds_read_b128 v[220:223], v158 offset:39936
	s_waitcnt lgkmcnt(0)
	s_branch .Lm64_Jb
.Lm64_Tb:
	s_add_i32 m0, s70, 0x8000
	s_add_u32 s62, s72, 0x80
	s_addc_u32 s63, s73, 0
	v_lshl_add_u64 v[152:153], s[62:63], 0, v[140:141]
	global_load_lds_dwordx4 v[152:153], off
	s_add_i32 m0, s70, 0x8400
	s_add_u32 s62, s72, 0xc0
	s_addc_u32 s63, s73, 0
	v_lshl_add_u64 v[152:153], s[62:63], 0, v[140:141]
	global_load_lds_dwordx4 v[152:153], off
	s_add_i32 m0, s70, 0x6000
	s_add_u32 s62, s72, 0x180000
	s_addc_u32 s63, s73, 0
	v_lshl_add_u64 v[152:153], s[62:63], 0, v[140:141]
	global_load_lds_dwordx4 v[152:153], off
	s_add_i32 m0, s70, 0x6400
	s_add_u32 s62, s72, 0x180040
	s_addc_u32 s63, s73, 0
	v_lshl_add_u64 v[152:153], s[62:63], 0, v[140:141]
	global_load_lds_dwordx4 v[152:153], off
	v_add_u32_e32 v159, 0x18000, v135
	ds_read_b128 v[148:151], v159
	ds_read_b128 v[160:163], v159 offset:1024
	ds_read_b128 v[164:167], v159 offset:2048
	ds_read_b128 v[168:171], v159 offset:3072
	v_add_u32_e32 v159, 0x1c000, v135
	ds_read_b128 v[176:179], v159
	ds_read_b128 v[180:183], v159 offset:1024
	ds_read_b128 v[184:187], v159 offset:2048
	ds_read_b128 v[188:191], v159 offset:3072
	ds_read_b128 v[192:195], v158 offset:32768
	ds_read_b128 v[196:199], v158 offset:33792
	ds_read_b128 v[200:203], v158 offset:34816
	ds_read_b128 v[204:207], v158 offset:35840
	ds_read_b128 v[208:211], v158 offset:36864
	ds_read_b128 v[212:215], v158 offset:37888
	ds_read_b128 v[216:219], v158 offset:38912
	ds_read_b128 v[220:223], v158 offset:39936
	s_waitcnt lgkmcnt(0)
	s_add_i32 m0, s71, 0x18000
	s_add_u32 s62, s74, 0x80
	s_addc_u32 s63, s75, 0
	v_lshl_add_u64 v[152:153], s[62:63], 0, v[142:143]
	global_load_lds_dwordx4 v[152:153], off
	s_add_i32 m0, s71, 0x18400
	s_add_u32 s62, s74, 0xc0
	s_addc_u32 s63, s75, 0
	v_lshl_add_u64 v[152:153], s[62:63], 0, v[142:143]
	global_load_lds_dwordx4 v[152:153], off
	s_add_i32 m0, s71, 0x18800
	s_add_u32 s62, s74, 0x8080
	s_addc_u32 s63, s75, 0
	v_lshl_add_u64 v[152:153], s[62:63], 0, v[142:143]
	global_load_lds_dwordx4 v[152:153], off
	s_add_i32 m0, s71, 0x18c00
	s_add_u32 s62, s74, 0x80c0
	s_addc_u32 s63, s75, 0
	v_lshl_add_u64 v[152:153], s[62:63], 0, v[142:143]
	global_load_lds_dwordx4 v[152:153], off
	s_waitcnt vmcnt(8)
.Lm64_Jb:
	s_barrier
	s_setprio 1
	v_mfma_f32_16x16x32_bf16 v[126:129], v[148:151], v[192:195], v[126:129]
	v_mfma_f32_16x16x32_bf16 v[122:125], v[164:167], v[192:195], v[122:125]
	v_mfma_f32_16x16x32_bf16 v[110:113], v[148:151], v[200:203], v[110:113]
	v_mfma_f32_16x16x32_bf16 v[106:109], v[164:167], v[200:203], v[106:109]
	v_mfma_f32_16x16x32_bf16 v[94:97], v[148:151], v[208:211], v[94:97]
	v_mfma_f32_16x16x32_bf16 v[90:93], v[164:167], v[208:211], v[90:93]
	v_mfma_f32_16x16x32_bf16 v[78:81], v[148:151], v[216:219], v[78:81]
	v_mfma_f32_16x16x32_bf16 v[74:77], v[164:167], v[216:219], v[74:77]
	v_mfma_f32_16x16x32_bf16 v[126:129], v[160:163], v[196:199], v[126:129]
	v_mfma_f32_16x16x32_bf16 v[122:125], v[168:171], v[196:199], v[122:125]
	v_mfma_f32_16x16x32_bf16 v[110:113], v[160:163], v[204:207], v[110:113]
	v_mfma_f32_16x16x32_bf16 v[106:109], v[168:171], v[204:207], v[106:109]
	v_mfma_f32_16x16x32_bf16 v[94:97], v[160:163], v[212:215], v[94:97]
	v_mfma_f32_16x16x32_bf16 v[90:93], v[168:171], v[212:215], v[90:93]
	v_mfma_f32_16x16x32_bf16 v[78:81], v[160:163], v[220:223], v[78:81]
	v_mfma_f32_16x16x32_bf16 v[74:77], v[168:171], v[220:223], v[74:77]
	v_mfma_f32_16x16x32_bf16 v[118:121], v[176:179], v[192:195], v[118:121]
	v_mfma_f32_16x16x32_bf16 v[114:117], v[184:187], v[192:195], v[114:117]
	v_mfma_f32_16x16x32_bf16 v[118:121], v[180:183], v[196:199], v[118:121]
	v_mfma_f32_16x16x32_bf16 v[114:117], v[188:191], v[196:199], v[114:117]
	ds_read_b128 v[192:195], v158 offset:49152
	ds_read_b128 v[196:199], v158 offset:50176
	v_mfma_f32_16x16x32_bf16 v[102:105], v[176:179], v[200:203], v[102:105]
	v_mfma_f32_16x16x32_bf16 v[98:101], v[184:187], v[200:203], v[98:101]
	v_mfma_f32_16x16x32_bf16 v[102:105], v[180:183], v[204:207], v[102:105]
	v_mfma_f32_16x16x32_bf16 v[98:101], v[188:191], v[204:207], v[98:101]
	ds_read_b128 v[200:203], v158 offset:51200
	ds_read_b128 v[204:207], v158 offset:52224
	v_mfma_f32_16x16x32_bf16 v[86:89], v[176:179], v[208:211], v[86:89]
	v_mfma_f32_16x16x32_bf16 v[82:85], v[184:187], v[208:211], v[82:85]
	v_mfma_f32_16x16x32_bf16 v[86:89], v[180:183], v[212:215], v[86:89]
	v_mfma_f32_16x16x32_bf16 v[82:85], v[188:191], v[212:215], v[82:85]
	ds_read_b128 v[208:211], v158 offset:53248
	ds_read_b128 v[212:215], v158 offset:54272
	v_mfma_f32_16x16x32_bf16 v[70:73], v[176:179], v[216:219], v[70:73]
	v_mfma_f32_16x16x32_bf16 v[66:69], v[184:187], v[216:219], v[66:69]
	v_mfma_f32_16x16x32_bf16 v[70:73], v[180:183], v[220:223], v[70:73]
	v_mfma_f32_16x16x32_bf16 v[66:69], v[188:191], v[220:223], v[66:69]
	ds_read_b128 v[216:219], v158 offset:55296
	ds_read_b128 v[220:223], v158 offset:56320
	s_waitcnt lgkmcnt(6)
	v_mfma_f32_16x16x32_bf16 v[62:65], v[148:151], v[192:195], v[62:65]
	v_mfma_f32_16x16x32_bf16 v[58:61], v[164:167], v[192:195], v[58:61]
	v_mfma_f32_16x16x32_bf16 v[62:65], v[160:163], v[196:199], v[62:65]
	v_mfma_f32_16x16x32_bf16 v[58:61], v[168:171], v[196:199], v[58:61]
	s_waitcnt lgkmcnt(4)
	v_mfma_f32_16x16x32_bf16 v[46:49], v[148:151], v[200:203], v[46:49]
	v_mfma_f32_16x16x32_bf16 v[42:45], v[164:167], v[200:203], v[42:45]
	v_mfma_f32_16x16x32_bf16 v[46:49], v[160:163], v[204:207], v[46:49]
	v_mfma_f32_16x16x32_bf16 v[42:45], v[168:171], v[204:207], v[42:45]
	s_waitcnt lgkmcnt(2)
	v_mfma_f32_16x16x32_bf16 v[30:33], v[148:151], v[208:211], v[30:33]
	v_mfma_f32_16x16x32_bf16 v[26:29], v[164:167], v[208:211], v[26:29]
	v_mfma_f32_16x16x32_bf16 v[30:33], v[160:163], v[212:215], v[30:33]
	v_mfma_f32_16x16x32_bf16 v[26:29], v[168:171], v[212:215], v[26:29]
	s_waitcnt lgkmcnt(0)
	v_mfma_f32_16x16x32_bf16 v[14:17], v[148:151], v[216:219], v[14:17]
	v_mfma_f32_16x16x32_bf16 v[10:13], v[164:167], v[216:219], v[10:13]
	v_mfma_f32_16x16x32_bf16 v[14:17], v[160:163], v[220:223], v[14:17]
	v_mfma_f32_16x16x32_bf16 v[10:13], v[168:171], v[220:223], v[10:13]
	v_mfma_f32_16x16x32_bf16 v[54:57], v[176:179], v[192:195], v[54:57]
	v_mfma_f32_16x16x32_bf16 v[50:53], v[184:187], v[192:195], v[50:53]
	v_mfma_f32_16x16x32_bf16 v[38:41], v[176:179], v[200:203], v[38:41]
	v_mfma_f32_16x16x32_bf16 v[34:37], v[184:187], v[200:203], v[34:37]
	v_mfma_f32_16x16x32_bf16 v[22:25], v[176:179], v[208:211], v[22:25]
	v_mfma_f32_16x16x32_bf16 v[18:21], v[184:187], v[208:211], v[18:21]
	v_mfma_f32_16x16x32_bf16 v[6:9], v[176:179], v[216:219], v[6:9]
	v_mfma_f32_16x16x32_bf16 v[2:5], v[184:187], v[216:219], v[2:5]
	v_mfma_f32_16x16x32_bf16 v[54:57], v[180:183], v[196:199], v[54:57]
	v_mfma_f32_16x16x32_bf16 v[50:53], v[188:191], v[196:199], v[50:53]
	v_mfma_f32_16x16x32_bf16 v[38:41], v[180:183], v[204:207], v[38:41]
	v_mfma_f32_16x16x32_bf16 v[34:37], v[188:191], v[204:207], v[34:37]
	v_mfma_f32_16x16x32_bf16 v[22:25], v[180:183], v[212:215], v[22:25]
	v_mfma_f32_16x16x32_bf16 v[18:21], v[188:191], v[212:215], v[18:21]
	v_mfma_f32_16x16x32_bf16 v[6:9], v[180:183], v[220:223], v[6:9]
	v_mfma_f32_16x16x32_bf16 v[2:5], v[188:191], v[220:223], v[2:5]
	s_setprio 0
	s_barrier
	s_add_i32 s61, s61, 2
	s_add_u32 s24, s24, 0x100
	s_addc_u32 s25, s25, 0
	s_add_u32 s22, s22, 0x100
	s_addc_u32 s23, s23, 0
	s_cmp_gt_u32 s61, 61
	s_cbranch_scc0 .LBB0_731
	v_and_b32_e32 v165, 3, v174
	v_lshrrev_b32_e32 v170, 2, v174
	v_lshlrev_b32_e32 v164, 6, v165
	v_and_or_b32 v164, v174, 60, v164
	v_and_b32_e32 v171, 15, v174
	v_sub_u32_e32 v170, v170, v171
	v_lshrrev_b32_e32 v171, 4, v174
	v_sub_u32_e32 v165, v165, v171
	v_mul_i32_i24_e32 v170, 0xac00, v170
	v_lshl_add_u32 v166, v165, 4, v170
	v_ashrrev_i32_e32 v167, 31, v166
	s_lshl_b32 s5, s56, 8
	s_add_i32 s5, s5, s39
	v_or_b32_e32 v159, s5, v1
	v_cmp_lt_i32_e64 s[0:1], s46, v159
	s_and_b64 s[22:23], s[0:1], s[18:19]
	v_mov_b64_e32 v[150:151], 0
	s_and_saveexec_b64 s[0:1], s[22:23]
	v_add_u32_e32 v148, 0xffffe000, v159
	v_lshrrev_b32_e32 v148, 2, v148
	v_and_b32_e32 v148, 0x3ffffff2, v148
	v_add_u32_e32 v150, v148, v154
	v_mov_b64_e32 v[148:149], s[10:11]
	v_mad_u64_u32 v[150:151], s[22:23], v150, s47, v[148:149]
	s_or_b64 exec, exec, s[0:1]
	v_lshl_or_b32 v148, s55, 8, v155
	v_mov_b64_e32 v[152:153], s[6:7]
	v_ashrrev_i32_e32 v149, 31, v148
	v_mad_i64_i32 v[152:153], s[0:1], v159, s48, v[152:153]
	v_lshl_add_u64 v[152:153], v[148:149], 1, v[152:153]
	v_cmp_ne_u64_e64 s[0:1], 0, v[150:151]
	v_lshl_add_u64 v[150:151], v[148:149], 2, v[150:151]
	v_cvt_pk_bf16_f32 v160, v126, v127
	v_cvt_pk_bf16_f32 v161, v128, v129
	v_cvt_pk_bf16_f32 v162, v122, v123
	v_cvt_pk_bf16_f32 v163, v124, v125
	ds_bpermute_b32 v160, v164, v160
	ds_bpermute_b32 v161, v164, v161
	ds_bpermute_b32 v162, v164, v162
	ds_bpermute_b32 v163, v164, v163
	v_lshl_add_u64 v[168:169], v[166:167], 0, v[152:153]
	s_waitcnt lgkmcnt(0)
	global_store_dwordx4 v[168:169], v[160:163], off
	s_and_saveexec_b64 s[22:23], s[0:1]
	s_cbranch_execz .LBB0_736
	global_store_dwordx4 v[150:151], v[126:129], off
	global_store_dwordx4 v[150:151], v[122:125], off offset:16
